# static s_setprio 1 on waves 0-3 instead of waves 4-7 (per-block flips still deleted)
# speedup vs baseline: 1.0053x; 1.0053x over previous
_Z6mk_fwd4Args:
	s_mov_b32 s10, s2
	s_load_dword s2, s[0:1], 0xf8
	s_load_dwordx8 s[84:91], s[0:1], 0xc0
	s_load_dwordx4 s[92:95], s[0:1], 0xe0
	s_load_dwordx2 s[80:81], s[0:1], 0xf0
	s_add_u32 s4, s0, 0xf0
	v_and_b32_e32 v174, 0x3ff, v0
	s_waitcnt lgkmcnt(0)
	v_writelane_b32 v243, s2, 0
	s_addc_u32 s5, s1, 0
	v_readfirstlane_b32 s2, v174
	v_cmp_gt_u32_e32 vcc, 2, v174
	s_nop 0
	v_writelane_b32 v243, s2, 1
	s_cmpk_ge_u32 s2, 0x100
	s_cbranch_scc1 .Lprio_done
	s_setprio 1
